# attention items: static XCD-aware raster (the 32 query blocks of one batch/head K/V set run on one XCD; two long items per workgroup, dynamic queue for the rest)
# speedup vs baseline: 1.0413x; 1.0023x over previous
.LBB0_540:
	s_or_b64 exec, exec, s[0:1]
	s_lshl_b32 s22, s16, 1
	s_lshl_b64 s[0:1], s[22:23], 2
	s_add_u32 s10, s30, s0
	s_addc_u32 s11, s31, s1
	s_lshl_b32 s4, s16, 8
	s_mov_b32 s5, s23
	s_mov_b32 s6, s4
	v_writelane_b32 v252, s6, 40
	s_lshl_b64 s[4:5], s[4:5], 2
	v_readlane_b32 s52, v253, 15
	v_writelane_b32 v252, s7, 41
	s_add_u32 s6, s78, s4
	s_addc_u32 s7, s79, s5
	v_writelane_b32 v252, s6, 42
	v_readlane_b32 s56, v253, 19
	v_readlane_b32 s53, v253, 16
	v_writelane_b32 v252, s7, 43
	s_add_u32 s6, s80, s4
	s_addc_u32 s7, s81, s5
	v_writelane_b32 v252, s6, 44
	v_readlane_b32 s57, v253, 20
	v_readlane_b32 s58, v253, 21
	v_writelane_b32 v252, s7, 45
	s_lshl_b32 s6, s16, 10
	s_mov_b32 s7, s23
	s_lshl_b64 s[6:7], s[6:7], 2
	s_add_u32 s52, s56, s6
	s_addc_u32 s53, s57, s7
	v_readlane_b32 s59, v253, 22
	s_add_u32 s56, s58, s4
	s_addc_u32 s57, s59, s5
	s_lshl_b32 s4, s16, 4
	v_writelane_b32 v252, s4, 46
	s_or_b32 s4, s4, 4
	v_readlane_b32 s66, v253, 29
	v_writelane_b32 v252, s4, 47
	s_lshl_b64 s[4:5], s[8:9], 2
	v_readlane_b32 s67, v253, 30
	s_add_u32 s6, s66, s4
	s_addc_u32 s7, s67, s5
	v_writelane_b32 v252, s6, 48
	v_readlane_b32 s62, v253, 25
	v_readlane_b32 s63, v253, 26
	v_writelane_b32 v252, s7, 49
	s_add_u32 s6, s68, s4
	s_addc_u32 s7, s69, s5
	v_writelane_b32 v252, s6, 50
	s_add_u32 s4, s62, s4
	s_addc_u32 s5, s63, s5
	v_writelane_b32 v252, s7, 51
	v_writelane_b32 v252, s4, 52
	v_readlane_b32 s54, v253, 17
	v_readlane_b32 s55, v253, 18
	v_writelane_b32 v252, s5, 53
	s_or_b32 s4, s22, 1
	s_lshl_b32 s5, s4, 3
	v_writelane_b32 v252, s5, 54
	s_or_b32 s5, s5, 4
	s_lshl_b32 s22, s4, 8
	v_writelane_b32 v252, s5, 55
	s_lshl_b64 s[4:5], s[22:23], 2
	s_add_u32 s6, s66, s4
	s_addc_u32 s7, s67, s5
	v_writelane_b32 v252, s6, 56
	s_mov_b64 s[66:67], s[10:11]
	v_readlane_b32 s60, v253, 23
	v_writelane_b32 v252, s7, 57
	s_add_u32 s6, s68, s4
	s_addc_u32 s7, s69, s5
	v_writelane_b32 v252, s6, 58
	s_add_u32 s4, s62, s4
	s_addc_u32 s5, s63, s5
	v_writelane_b32 v252, s7, 59
	v_writelane_b32 v252, s4, 60
	v_readlane_b32 s61, v253, 24
	v_readlane_b32 s64, v253, 27
	v_writelane_b32 v252, s5, 61
	v_readlane_b32 s65, v253, 28
	v_readlane_b32 s4, v252, 13
	s_add_u32 s62, s4, s0
	v_readlane_b32 s0, v252, 14
	s_addc_u32 s63, s0, s1
	s_lshl_b32 s22, s16, 6
	v_readlane_b32 s4, v253, 1
	s_lshl_b64 s[58:59], s[22:23], 2
	v_readlane_b32 s10, v253, 7
	v_readlane_b32 s11, v253, 8
	s_add_u32 s34, s10, s58
	v_readlane_b32 s54, v252, 34
	v_readlane_b32 s60, v252, 36
	v_readlane_b32 s64, v252, 38
	s_addc_u32 s35, s11, s59
	v_readlane_b32 s55, v252, 35
	v_readlane_b32 s61, v252, 37
	v_readlane_b32 s65, v252, 39
	s_waitcnt lgkmcnt(0)
	s_barrier
	v_readlane_b32 s5, v253, 2
	v_readlane_b32 s6, v253, 3
	v_readlane_b32 s7, v253, 4
	v_readlane_b32 s8, v253, 5
	v_readlane_b32 s9, v253, 6
	v_readlane_b32 s0, v253, 0
	s_and_b32 s1, s0, 7
	s_lshl_b32 s1, s1, 1
	s_lshr_b32 vcc_lo, s0, 8
	s_or_b32 s1, s1, vcc_lo
	s_lshl_b32 s1, s1, 5
	s_bfe_u32 vcc_lo, s0, 0x50003
	s_or_b32 s1, s1, vcc_lo
	v_mov_b32_e32 v255, s1
	s_branch .LBB0_544

.LBB0_544:
	s_barrier
	s_and_saveexec_b64 s[0:1], s[14:15]
	s_cbranch_execz .LBB0_548
	v_cmp_le_i32_e32 vcc, 0, v255
	s_cbranch_vccnz .Lar_static
	v_mov_b32_e32 v255, 1
	global_atomic_add v255, v3, v255, s[66:67] sc0
	s_waitcnt vmcnt(0)
	v_add_u32_e32 v0, 0x400, v255
	v_mov_b32_e32 v255, -1
	s_branch .Lar_have
.Lar_static:
	v_mov_b32_e32 v0, v255
	v_cmp_gt_u32_e32 vcc, 0x200, v0
	v_add_u32_e32 v255, 0x200, v0
	v_cndmask_b32_e32 v255, -1, v255, vcc
.Lar_have:
	ds_write_b32 v3, v0 offset:16
